# mLSTM chunk loop: the gate-scan wave raises its issue priority while it scans (reset when it rejoins the common path)
# speedup vs baseline: 1.0086x; 1.0033x over previous
.LBB0_671:
	s_andn2_b64 vcc, exec, s[74:75]
	s_cbranch_vccnz .LBB0_675
	s_setprio 2
	ds_read_b64 v[2:3], v156
	v_max_f32_e32 v4, v171, v171
	s_waitcnt lgkmcnt(0)
	v_max_f32_e32 v1, v3, v3
	s_nop 1
	v_max_f32_dpp v1, v1, v1 row_shr:1 row_mask:0xf bank_mask:0xf
	s_nop 1
	v_max_f32_dpp v1, v1, v1 row_shr:2 row_mask:0xf bank_mask:0xf
	s_nop 1
	v_max_f32_dpp v1, v1, v1 row_shr:4 row_mask:0xf bank_mask:0xf
	s_nop 1
	v_max_f32_dpp v1, v1, v1 row_shr:8 row_mask:0xf bank_mask:0xf
	s_nop 1
	v_max_f32_dpp v1, v1, v1 row_bcast:15 row_mask:0xa bank_mask:0xf
	s_nop 1
	v_max_f32_dpp v1, v1, v1 row_bcast:31 row_mask:0xc bank_mask:0xf
	s_nop 1
	ds_bpermute_b32 v3, v130, v1
	ds_bpermute_b32 v0, v130, v2
	v_max_f32_e32 v1, v1, v1
	v_max_f32_e32 v1, v4, v1
	v_add_f32_e32 v1, v2, v1
	s_waitcnt lgkmcnt(1)
	v_max_f32_e32 v3, v3, v3
	v_sub_f32_e32 v2, v2, v1
	v_max_f32_e32 v3, v4, v3
	s_waitcnt lgkmcnt(0)
	v_add_f32_e32 v172, v3, v0
	v_mul_f32_e32 v3, 0x3fb8aa3b, v2
	v_add_f32_e32 v2, v171, v2
	v_mul_f32_e32 v2, 0x3fb8aa3b, v2
	v_mul_f32_e32 v1, 0xbfb8aa3b, v1
	v_exp_f32_e32 v3, v3
	v_exp_f32_e32 v2, v2
	v_exp_f32_e32 v1, v1
	ds_write2st64_b32 v137, v3, v2 offset1:1
	ds_write_b32 v137, v1 offset:512
	s_and_saveexec_b64 s[4:5], s[10:11]
	s_cbranch_execz .LBB0_674
	v_sub_f32_e32 v1, v0, v172
	v_add_f32_e32 v0, v171, v0
	v_sub_f32_e32 v0, v0, v172
	v_mul_f32_e32 v1, 0x3fb8aa3b, v1
	v_mul_f32_e32 v0, 0x3fb8aa3b, v0
	v_exp_f32_e32 v1, v1
	v_exp_f32_e32 v0, v0
	v_mov_b32_e32 v2, s3
	ds_write_b64 v2, v[0:1]

.LBB0_676:
	s_setprio 0
	ds_read_b128 v[0:3], v131
	ds_read_b128 v[4:7], v131 offset:16
	ds_read_b128 v[8:11], v132
	ds_read_b128 v[12:15], v132 offset:16
	ds_read_b128 v[56:59], v132 offset:32
	ds_read_b128 v[60:63], v132 offset:48
	s_waitcnt lgkmcnt(5)
	v_lshlrev_b32_e32 v64, 16, v0
	v_and_b32_e32 v0, 0xffff0000, v0
	s_waitcnt lgkmcnt(3)
	v_mul_f32_e32 v0, v9, v0
	v_fmac_f32_e32 v0, v8, v64
	v_lshlrev_b32_e32 v8, 16, v1
	v_fmac_f32_e32 v0, v10, v8
	v_and_b32_e32 v1, 0xffff0000, v1
	v_fmac_f32_e32 v0, v11, v1
	v_lshlrev_b32_e32 v1, 16, v2
	s_waitcnt lgkmcnt(2)
	v_fmac_f32_e32 v0, v12, v1
	v_and_b32_e32 v1, 0xffff0000, v2
	v_fmac_f32_e32 v0, v13, v1
	v_lshlrev_b32_e32 v1, 16, v3
	v_fmac_f32_e32 v0, v14, v1
	v_and_b32_e32 v1, 0xffff0000, v3
	v_and_b32_e32 v2, 0xffff0000, v4
	v_fmac_f32_e32 v0, v15, v1
	v_lshlrev_b32_e32 v1, 16, v4
	s_waitcnt lgkmcnt(1)
	v_mul_f32_e32 v2, v57, v2
	v_fmac_f32_e32 v2, v56, v1
	v_lshlrev_b32_e32 v1, 16, v5
	v_fmac_f32_e32 v2, v58, v1
	v_and_b32_e32 v1, 0xffff0000, v5
	v_fmac_f32_e32 v2, v59, v1
	v_lshlrev_b32_e32 v1, 16, v6
	s_waitcnt lgkmcnt(0)
	v_fmac_f32_e32 v2, v60, v1
	v_and_b32_e32 v1, 0xffff0000, v6
	v_fmac_f32_e32 v2, v61, v1
	v_lshlrev_b32_e32 v1, 16, v7
	v_fmac_f32_e32 v2, v62, v1
	v_and_b32_e32 v1, 0xffff0000, v7
	v_add_f32_e32 v0, 0, v0
	v_fmac_f32_e32 v2, v63, v1
	v_add_f32_e32 v0, v0, v2
	s_nop 1
	v_add_f32_dpp v0, v0, v0 quad_perm:[1,0,3,2] row_mask:0xf bank_mask:0xf
	s_nop 1
	v_add_f32_dpp v0, v0, v0 quad_perm:[2,3,0,1] row_mask:0xf bank_mask:0xf
	s_nop 1
	v_mov_b32_dpp v1, v0 row_half_mirror row_mask:0xf bank_mask:0xf
	s_and_saveexec_b64 s[4:5], s[8:9]
	s_cbranch_execz .LBB0_678
	s_waitcnt lgkmcnt(0)
	v_add_f32_e32 v0, v0, v1
	ds_write_b32 v138, v0

.LBB0_699:
	s_waitcnt lgkmcnt(0)
	s_barrier
	s_and_b64 s[70:71], s[74:75], s[96:97]
	s_andn2_b64 vcc, exec, s[70:71]
	s_cbranch_vccnz .LBB0_703
	s_setprio 2
	ds_read_b64 v[2:3], v156 offset:512
	v_max_f32_e32 v4, v172, v172
	s_waitcnt lgkmcnt(0)
	v_max_f32_e32 v1, v3, v3
	s_nop 1
	v_max_f32_dpp v1, v1, v1 row_shr:1 row_mask:0xf bank_mask:0xf
	s_nop 1
	v_max_f32_dpp v1, v1, v1 row_shr:2 row_mask:0xf bank_mask:0xf
	s_nop 1
	v_max_f32_dpp v1, v1, v1 row_shr:4 row_mask:0xf bank_mask:0xf
	s_nop 1
	v_max_f32_dpp v1, v1, v1 row_shr:8 row_mask:0xf bank_mask:0xf
	s_nop 1
	v_max_f32_dpp v1, v1, v1 row_bcast:15 row_mask:0xa bank_mask:0xf
	s_nop 1
	v_max_f32_dpp v1, v1, v1 row_bcast:31 row_mask:0xc bank_mask:0xf
	s_nop 1
	ds_bpermute_b32 v3, v130, v1
	ds_bpermute_b32 v0, v130, v2
	v_max_f32_e32 v1, v1, v1
	v_max_f32_e32 v1, v4, v1
	v_add_f32_e32 v1, v2, v1
	s_waitcnt lgkmcnt(1)
	v_max_f32_e32 v3, v3, v3
	v_sub_f32_e32 v2, v2, v1
	v_max_f32_e32 v3, v4, v3
	s_waitcnt lgkmcnt(0)
	v_add_f32_e32 v171, v3, v0
	v_mul_f32_e32 v3, 0x3fb8aa3b, v2
	v_add_f32_e32 v2, v172, v2
	v_mul_f32_e32 v2, 0x3fb8aa3b, v2
	v_mul_f32_e32 v1, 0xbfb8aa3b, v1
	v_exp_f32_e32 v3, v3
	v_exp_f32_e32 v2, v2
	v_exp_f32_e32 v1, v1
	ds_write2st64_b32 v153, v3, v2 offset1:1
	ds_write_b32 v153, v1 offset:512
	s_and_saveexec_b64 s[70:71], s[10:11]
	s_cbranch_execz .LBB0_702
	v_sub_f32_e32 v1, v0, v171
	v_add_f32_e32 v0, v172, v0
	v_sub_f32_e32 v0, v0, v171
	v_mul_f32_e32 v1, 0x3fb8aa3b, v1
	v_mul_f32_e32 v0, 0x3fb8aa3b, v0
	v_exp_f32_e32 v1, v1
	v_exp_f32_e32 v0, v0
	v_mov_b32_e32 v2, s78
	ds_write_b64 v2, v[0:1]

.LBB0_704:
	s_setprio 0
	ds_read_b128 v[0:3], v131
	ds_read_b128 v[4:7], v131 offset:16
	ds_read_b128 v[8:11], v132
	ds_read_b128 v[12:15], v132 offset:16
	ds_read_b128 v[56:59], v132 offset:32
	ds_read_b128 v[60:63], v132 offset:48
	s_waitcnt lgkmcnt(5)
	v_lshlrev_b32_e32 v64, 16, v0
	v_and_b32_e32 v0, 0xffff0000, v0
	s_waitcnt lgkmcnt(3)
	v_mul_f32_e32 v0, v9, v0
	v_fmac_f32_e32 v0, v8, v64
	v_lshlrev_b32_e32 v8, 16, v1
	v_fmac_f32_e32 v0, v10, v8
	v_and_b32_e32 v1, 0xffff0000, v1
	v_fmac_f32_e32 v0, v11, v1
	v_lshlrev_b32_e32 v1, 16, v2
	s_waitcnt lgkmcnt(2)
	v_fmac_f32_e32 v0, v12, v1
	v_and_b32_e32 v1, 0xffff0000, v2
	v_fmac_f32_e32 v0, v13, v1
	v_lshlrev_b32_e32 v1, 16, v3
	v_fmac_f32_e32 v0, v14, v1
	v_and_b32_e32 v1, 0xffff0000, v3
	v_and_b32_e32 v2, 0xffff0000, v4
	v_fmac_f32_e32 v0, v15, v1
	v_lshlrev_b32_e32 v1, 16, v4
	s_waitcnt lgkmcnt(1)
	v_mul_f32_e32 v2, v57, v2
	v_fmac_f32_e32 v2, v56, v1
	v_lshlrev_b32_e32 v1, 16, v5
	v_fmac_f32_e32 v2, v58, v1
	v_and_b32_e32 v1, 0xffff0000, v5
	v_fmac_f32_e32 v2, v59, v1
	v_lshlrev_b32_e32 v1, 16, v6
	s_waitcnt lgkmcnt(0)
	v_fmac_f32_e32 v2, v60, v1
	v_and_b32_e32 v1, 0xffff0000, v6
	v_fmac_f32_e32 v2, v61, v1
	v_lshlrev_b32_e32 v1, 16, v7
	v_fmac_f32_e32 v2, v62, v1
	v_and_b32_e32 v1, 0xffff0000, v7
	v_add_f32_e32 v0, 0, v0
	v_fmac_f32_e32 v2, v63, v1
	v_add_f32_e32 v0, v0, v2
	s_nop 1
	v_add_f32_dpp v0, v0, v0 quad_perm:[1,0,3,2] row_mask:0xf bank_mask:0xf
	s_nop 1
	v_add_f32_dpp v0, v0, v0 quad_perm:[2,3,0,1] row_mask:0xf bank_mask:0xf
	s_nop 1
	v_mov_b32_dpp v1, v0 row_half_mirror row_mask:0xf bank_mask:0xf
	s_and_saveexec_b64 s[70:71], s[8:9]
	s_cbranch_execz .LBB0_706
	s_waitcnt lgkmcnt(0)
	v_add_f32_e32 v0, v0, v1
	ds_write_b32 v138, v0
